# GEMM K-loop: first-iteration vmcnt relaxed by the epilogue's stores (vmcnt(16) in phases 1-2 after a tile epilogue)
# speedup vs baseline: 1.0097x; 1.0017x over previous
; #define PG8_STAGE(bufoff, gbase, voff) do { _Pragma("unroll") for (int _i = 0; _i < 2; ++_i) \
;         __builtin_amdgcn_global_load_lds((const unsigned*)((const char*)(gbase) + (voff)[_i]), (LAS unsigned*)(lds + (bufoff) + ldsw + _i * 8192), 16, 0, 0); } while (0)
; #define PG8_LDA(dst, b, h) do { _Pragma("unroll") for (int m = 0; m < 4; ++m) _Pragma("unroll") for (int k = 0; k < 2; ++k) dst[m][k] = *(const LAS bf16x8*)(lds + PG8_SA(b, h) + aoff + m * 2048 + k * 1024); } while (0)
; #define PG8_LDB(dst, b, h) do { _Pragma("unroll") for (int n = 0; n < 2; ++n) _Pragma("unroll") for (int k = 0; k < 2; ++k) dst[n][k] = *(const LAS bf16x8*)(lds + PG8_SB(b, h) + boff + n * 2048 + k * 1024); } while (0)
; #define PG8_MMA(ai, bj, At, Bt) do { __builtin_amdgcn_s_setprio(1); _Pragma("unroll") for (int m = 0; m < 4; ++m) _Pragma("unroll") for (int n = 0; n < 2; ++n) _Pragma("unroll") for (int k = 0; k < 2; ++k) \
;         acc[ai][bj][m][n] = __builtin_amdgcn_mfma_f32_16x16x32_bf16(Bt[n][k], At[m][k], acc[ai][bj][m][n], 0, 0, 0); __builtin_amdgcn_s_setprio(0); } while (0)
; #define PG8_WAIT_V(n) asm volatile("s_waitcnt vmcnt(" #n ")" ::: "memory")
; #define PG8_WAIT_L(n) asm volatile("s_waitcnt lgkmcnt(" #n ")" ::: "memory")
; #define PG8_BAR __builtin_amdgcn_s_barrier()
; #define PG8_SCHED __builtin_amdgcn_sched_barrier(0)
; __device__ __forceinline__ void gemm_phase(LAS unsigned char* lds, const Gemm g, const StaticOrder& S, const Epi& E, const int tid) {
;     ...
;         for (int t = 0; t < nt; t += 2) {
;             const bool last = (t == nt - 2);
;             const char* a1 = cA + (size_t)(t + 1) * kstep;
;             const char* a2 = last ? nA : cA + (size_t)(t + 2) * kstep; const char* b2 = last ? nB : cB + (size_t)(t + 2) * kstep;
;             const char* a3 = a2 + kstep; const char* b3 = b2 + kstep;
;             PG8_LDB(B0, 0, 0); PG8_LDB(B1, 0, 1); PG8_SCHED; PG8_LDA(At, 0, 0); PG8_STAGE(PG8_SA(1, 1), a1 + hstepA, voffA);
;             PG8_WAIT_V(8); PG8_WAIT_L(0); PG8_BAR; PG8_MMA(0, 0, At, B0); PG8_MMA(0, 1, At, B1); PG8_BAR; PG8_SCHED;
;             PG8_LDA(At, 0, 1); PG8_STAGE(PG8_SB(0, 0), b2, voffB); PG8_STAGE(PG8_SB(0, 1), b2 + hstepB, voffB); PG8_STAGE(PG8_SA(0, 0), a2, voffA);
;             PG8_WAIT_V(8); PG8_WAIT_L(0); PG8_BAR; PG8_MMA(1, 0, At, B0); PG8_MMA(1, 1, At, B1); PG8_BAR; PG8_SCHED;
.LBB0_530:
	s_add_i32 s29, s4, 2
	s_add_u32 s24, s2, 0x80
	s_addc_u32 s5, s3, 0
	s_add_i32 s25, 0, 0x10000
	s_cmp_eq_u32 s15, s4
	s_cselect_b32 s5, s13, s5
	s_cselect_b32 s4, s12, s24
	s_cselect_b32 s61, s27, s19
	s_cselect_b32 s60, s26, s18
	s_add_i32 s24, 0, 0x14000
	v_add_u32_e32 v142, s25, v192
	v_add_u32_e32 v158, s24, v192
	ds_read_b128 v[130:133], v142
	ds_read_b128 v[134:137], v142 offset:1024
	ds_read_b128 v[138:141], v142 offset:2048
	ds_read_b128 v[142:145], v142 offset:3072
	ds_read_b128 v[146:149], v158
	ds_read_b128 v[150:153], v158 offset:1024
	ds_read_b128 v[154:157], v158 offset:2048
	ds_read_b128 v[158:161], v158 offset:3072
	v_lshl_add_u64 v[188:189], s[2:3], 0, v[184:185]
	s_add_i32 m0, s73, 0xc000
	ds_read_b128 v[162:165], v219
	ds_read_b128 v[166:169], v219 offset:1024
	ds_read_b128 v[170:173], v219 offset:2048
	ds_read_b128 v[174:177], v219 offset:3072
	ds_read_b128 v[220:223], v219 offset:4096
	ds_read_b128 v[224:227], v219 offset:5120
	ds_read_b128 v[228:231], v219 offset:6144
	ds_read_b128 v[232:235], v219 offset:7168
	global_load_lds_dwordx4 v[188:189], off
	v_lshl_add_u64 v[188:189], s[2:3], 0, v[186:187]
	s_add_i32 m0, s73, 0xe000
	s_nop 0
	global_load_lds_dwordx4 v[188:189], off
	s_cmp_lg_u32 s29, 2
	s_cbranch_scc1 .Lk1_std
	s_cmp_lt_u32 s9, 2
	s_cbranch_scc1 .Lk1_std
	s_waitcnt vmcnt(16)
	s_branch .Lk1_done
.Lk1_std:
	s_waitcnt vmcnt(8)
.Lk1_done:
	s_waitcnt lgkmcnt(0)
	s_barrier
	s_setprio 1
	s_waitcnt lgkmcnt(0)
	v_mfma_f32_16x16x32_bf16 v[118:121], v[130:133], v[162:165], v[118:121]
	v_mfma_f32_16x16x32_bf16 v[110:113], v[138:141], v[162:165], v[110:113]
	v_mfma_f32_16x16x32_bf16 v[102:105], v[130:133], v[170:173], v[102:105]
	v_mfma_f32_16x16x32_bf16 v[94:97], v[138:141], v[170:173], v[94:97]
	v_mfma_f32_16x16x32_bf16 v[86:89], v[130:133], v[220:223], v[86:89]
	v_mfma_f32_16x16x32_bf16 v[74:77], v[138:141], v[220:223], v[74:77]
	v_mfma_f32_16x16x32_bf16 v[82:85], v[130:133], v[228:231], v[82:85]
	v_mfma_f32_16x16x32_bf16 v[70:73], v[138:141], v[228:231], v[70:73]
	v_mfma_f32_16x16x32_bf16 v[118:121], v[134:137], v[166:169], v[118:121]
	v_mfma_f32_16x16x32_bf16 v[110:113], v[142:145], v[166:169], v[110:113]
	v_mfma_f32_16x16x32_bf16 v[102:105], v[134:137], v[174:177], v[102:105]
	v_mfma_f32_16x16x32_bf16 v[94:97], v[142:145], v[174:177], v[94:97]
	v_mfma_f32_16x16x32_bf16 v[86:89], v[134:137], v[224:227], v[86:89]
	v_mfma_f32_16x16x32_bf16 v[74:77], v[142:145], v[224:227], v[74:77]
	v_mfma_f32_16x16x32_bf16 v[82:85], v[134:137], v[232:235], v[82:85]
	v_mfma_f32_16x16x32_bf16 v[70:73], v[142:145], v[232:235], v[70:73]
	s_setprio 0
	s_setprio 1
	v_mfma_f32_16x16x32_bf16 v[126:129], v[146:149], v[162:165], v[126:129]
	v_mfma_f32_16x16x32_bf16 v[122:125], v[154:157], v[162:165], v[122:125]
	v_mfma_f32_16x16x32_bf16 v[114:117], v[146:149], v[170:173], v[114:117]
	v_mfma_f32_16x16x32_bf16 v[106:109], v[154:157], v[170:173], v[106:109]
	v_mfma_f32_16x16x32_bf16 v[98:101], v[146:149], v[220:223], v[98:101]
	v_mfma_f32_16x16x32_bf16 v[90:93], v[154:157], v[220:223], v[90:93]
	v_mfma_f32_16x16x32_bf16 v[78:81], v[146:149], v[228:231], v[78:81]
	v_mfma_f32_16x16x32_bf16 v[66:69], v[154:157], v[228:231], v[66:69]
	v_mfma_f32_16x16x32_bf16 v[126:129], v[150:153], v[166:169], v[126:129]
	v_mfma_f32_16x16x32_bf16 v[122:125], v[158:161], v[166:169], v[122:125]
	v_mfma_f32_16x16x32_bf16 v[114:117], v[150:153], v[174:177], v[114:117]
	v_mfma_f32_16x16x32_bf16 v[106:109], v[158:161], v[174:177], v[106:109]
	v_mfma_f32_16x16x32_bf16 v[98:101], v[150:153], v[224:227], v[98:101]
	v_mfma_f32_16x16x32_bf16 v[90:93], v[158:161], v[224:227], v[90:93]
	v_mfma_f32_16x16x32_bf16 v[78:81], v[150:153], v[232:235], v[78:81]
	v_mfma_f32_16x16x32_bf16 v[66:69], v[158:161], v[232:235], v[66:69]
	s_setprio 0
	s_barrier
	s_add_i32 s25, s25, s72
	v_lshl_add_u64 v[188:189], s[60:61], 0, v[0:1]
	s_mov_b32 m0, s25
	ds_read_b128 v[162:165], v219 offset:16384
	ds_read_b128 v[166:169], v219 offset:17408
	ds_read_b128 v[170:173], v219 offset:18432
	ds_read_b128 v[174:177], v219 offset:19456
	ds_read_b128 v[220:223], v219 offset:20480
	ds_read_b128 v[224:227], v219 offset:21504
	ds_read_b128 v[228:231], v219 offset:22528
	ds_read_b128 v[232:235], v219 offset:23552
	global_load_lds_dwordx4 v[188:189], off
	s_add_i32 m0, s25, 0x2000
	v_lshl_add_u64 v[236:237], s[60:61], 0, v[182:183]
	s_add_u32 s60, s60, s66
	s_addc_u32 s61, s61, s67
	s_add_i32 s24, s24, s72
	global_load_lds_dwordx4 v[236:237], off
	v_lshl_add_u64 v[238:239], s[60:61], 0, v[0:1]
	s_mov_b32 m0, s24
	v_lshl_add_u64 v[240:241], s[60:61], 0, v[182:183]
	global_load_lds_dwordx4 v[238:239], off
	s_add_i32 m0, s24, 0x2000
	v_lshl_add_u64 v[242:243], s[4:5], 0, v[178:179]
	global_load_lds_dwordx4 v[240:241], off
	s_mov_b32 m0, s73
	v_lshl_add_u64 v[244:245], s[4:5], 0, v[180:181]
	global_load_lds_dwordx4 v[242:243], off
	s_mov_b32 m0, s74
	s_nop 0
	global_load_lds_dwordx4 v[244:245], off
	s_cmp_lg_u32 s29, 2
	s_cbranch_scc1 .Lk2_std
	s_cmp_lt_u32 s9, 2
	s_cbranch_scc1 .Lk2_std
	s_waitcnt vmcnt(16)
	s_branch .Lk2_done

; #define PG8_STAGE(bufoff, gbase, voff) do { _Pragma("unroll") for (int _i = 0; _i < 2; ++_i) \
;         __builtin_amdgcn_global_load_lds((const unsigned*)((const char*)(gbase) + (voff)[_i]), (LAS unsigned*)(lds + (bufoff) + ldsw + _i * 8192), 16, 0, 0); } while (0)
; #define PG8_LDA(dst, b, h) do { _Pragma("unroll") for (int m = 0; m < 4; ++m) _Pragma("unroll") for (int k = 0; k < 2; ++k) dst[m][k] = *(const LAS bf16x8*)(lds + PG8_SA(b, h) + aoff + m * 2048 + k * 1024); } while (0)
; #define PG8_LDB(dst, b, h) do { _Pragma("unroll") for (int n = 0; n < 2; ++n) _Pragma("unroll") for (int k = 0; k < 2; ++k) dst[n][k] = *(const LAS bf16x8*)(lds + PG8_SB(b, h) + boff + n * 2048 + k * 1024); } while (0)
; #define PG8_MMA(ai, bj, At, Bt) do { __builtin_amdgcn_s_setprio(1); _Pragma("unroll") for (int m = 0; m < 4; ++m) _Pragma("unroll") for (int n = 0; n < 2; ++n) _Pragma("unroll") for (int k = 0; k < 2; ++k) \
;         acc[ai][bj][m][n] = __builtin_amdgcn_mfma_f32_16x16x32_bf16(Bt[n][k], At[m][k], acc[ai][bj][m][n], 0, 0, 0); __builtin_amdgcn_s_setprio(0); } while (0)
; #define PG8_WAIT_V(n) asm volatile("s_waitcnt vmcnt(" #n ")" ::: "memory")
; #define PG8_WAIT_L(n) asm volatile("s_waitcnt lgkmcnt(" #n ")" ::: "memory")
; #define PG8_BAR __builtin_amdgcn_s_barrier()
; #define PG8_SCHED __builtin_amdgcn_sched_barrier(0)
; __device__ __forceinline__ void gemm_phase(LAS unsigned char* lds, const Gemm g, const StaticOrder& S, const Epi& E, const int tid) {
;     ...
;             PG8_WAIT_V(8); PG8_WAIT_L(0); PG8_BAR; PG8_MMA(1, 0, At, B0); PG8_MMA(1, 1, At, B1); PG8_BAR; PG8_SCHED;
;             PG8_LDB(B0, 1, 0); PG8_LDB(B1, 1, 1); PG8_SCHED; PG8_LDA(At, 1, 0); PG8_STAGE(PG8_SA(0, 1), a2 + hstepA, voffA);
;             PG8_WAIT_V(8); PG8_WAIT_L(0); PG8_BAR; PG8_MMA(0, 0, At, B0); PG8_MMA(0, 1, At, B1); PG8_BAR; PG8_SCHED;
.Lk2_done:
	s_waitcnt lgkmcnt(0)
	s_barrier
	s_setprio 1
	s_waitcnt lgkmcnt(0)
	v_mfma_f32_16x16x32_bf16 v[54:57], v[130:133], v[162:165], v[54:57]
	v_mfma_f32_16x16x32_bf16 v[46:49], v[138:141], v[162:165], v[46:49]
	v_mfma_f32_16x16x32_bf16 v[38:41], v[130:133], v[170:173], v[38:41]
	v_mfma_f32_16x16x32_bf16 v[30:33], v[138:141], v[170:173], v[30:33]
	v_mfma_f32_16x16x32_bf16 v[22:25], v[130:133], v[220:223], v[22:25]
	v_mfma_f32_16x16x32_bf16 v[18:21], v[138:141], v[220:223], v[18:21]
	v_mfma_f32_16x16x32_bf16 v[14:17], v[130:133], v[228:231], v[14:17]
	v_mfma_f32_16x16x32_bf16 v[6:9], v[138:141], v[228:231], v[6:9]
	v_mfma_f32_16x16x32_bf16 v[54:57], v[134:137], v[166:169], v[54:57]
	v_mfma_f32_16x16x32_bf16 v[46:49], v[142:145], v[166:169], v[46:49]
	v_mfma_f32_16x16x32_bf16 v[38:41], v[134:137], v[174:177], v[38:41]
	v_mfma_f32_16x16x32_bf16 v[30:33], v[142:145], v[174:177], v[30:33]
	v_mfma_f32_16x16x32_bf16 v[22:25], v[134:137], v[224:227], v[22:25]
	v_mfma_f32_16x16x32_bf16 v[18:21], v[142:145], v[224:227], v[18:21]
	v_mfma_f32_16x16x32_bf16 v[14:17], v[134:137], v[232:235], v[14:17]
	v_mfma_f32_16x16x32_bf16 v[6:9], v[142:145], v[232:235], v[6:9]
	s_setprio 0
	s_setprio 1
	v_mfma_f32_16x16x32_bf16 v[62:65], v[146:149], v[162:165], v[62:65]
	v_mfma_f32_16x16x32_bf16 v[58:61], v[154:157], v[162:165], v[58:61]
	v_mfma_f32_16x16x32_bf16 v[50:53], v[146:149], v[170:173], v[50:53]
	v_mfma_f32_16x16x32_bf16 v[42:45], v[154:157], v[170:173], v[42:45]
	v_mfma_f32_16x16x32_bf16 v[34:37], v[146:149], v[220:223], v[34:37]
	v_mfma_f32_16x16x32_bf16 v[26:29], v[154:157], v[220:223], v[26:29]
	v_mfma_f32_16x16x32_bf16 v[10:13], v[146:149], v[228:231], v[10:13]
	v_mfma_f32_16x16x32_bf16 v[2:5], v[154:157], v[228:231], v[2:5]
	v_mfma_f32_16x16x32_bf16 v[62:65], v[150:153], v[166:169], v[62:65]
	v_mfma_f32_16x16x32_bf16 v[58:61], v[158:161], v[166:169], v[58:61]
	v_mfma_f32_16x16x32_bf16 v[50:53], v[150:153], v[174:177], v[50:53]
	v_mfma_f32_16x16x32_bf16 v[42:45], v[158:161], v[174:177], v[42:45]
	v_mfma_f32_16x16x32_bf16 v[34:37], v[150:153], v[224:227], v[34:37]
	v_mfma_f32_16x16x32_bf16 v[26:29], v[158:161], v[224:227], v[26:29]
	v_mfma_f32_16x16x32_bf16 v[10:13], v[150:153], v[232:235], v[10:13]
	v_mfma_f32_16x16x32_bf16 v[2:5], v[158:161], v[232:235], v[2:5]
	s_setprio 0
	s_barrier
	s_add_i32 s24, 0, 0x18000
	s_add_i32 s25, 0, 0x1c000
	v_add_u32_e32 v142, s24, v192
	v_add_u32_e32 v158, s25, v192
	ds_read_b128 v[130:133], v142
	ds_read_b128 v[134:137], v142 offset:1024
	ds_read_b128 v[138:141], v142 offset:2048
	ds_read_b128 v[142:145], v142 offset:3072
	ds_read_b128 v[146:149], v158
	ds_read_b128 v[150:153], v158 offset:1024
	ds_read_b128 v[154:157], v158 offset:2048
	ds_read_b128 v[158:161], v158 offset:3072
	s_add_u32 s4, s4, s66
	s_addc_u32 s5, s5, s67
	s_mov_b32 m0, s75
	v_lshl_add_u64 v[246:247], s[4:5], 0, v[178:179]
	ds_read_b128 v[162:165], v219 offset:32768
	ds_read_b128 v[166:169], v219 offset:33792
	ds_read_b128 v[170:173], v219 offset:34816
	ds_read_b128 v[174:177], v219 offset:35840
	ds_read_b128 v[220:223], v219 offset:36864
	ds_read_b128 v[224:227], v219 offset:37888
	ds_read_b128 v[228:231], v219 offset:38912
	ds_read_b128 v[232:235], v219 offset:39936
	global_load_lds_dwordx4 v[246:247], off
	v_lshl_add_u64 v[246:247], s[4:5], 0, v[180:181]
	s_mov_b32 m0, s91
	s_nop 0
	global_load_lds_dwordx4 v[246:247], off
	s_waitcnt vmcnt(8)
	s_waitcnt lgkmcnt(0)
	s_barrier
	s_setprio 1
	s_waitcnt lgkmcnt(0)
	v_mfma_f32_16x16x32_bf16 v[118:121], v[130:133], v[162:165], v[118:121]
	v_mfma_f32_16x16x32_bf16 v[110:113], v[138:141], v[162:165], v[110:113]
	v_mfma_f32_16x16x32_bf16 v[102:105], v[130:133], v[170:173], v[102:105]
	v_mfma_f32_16x16x32_bf16 v[94:97], v[138:141], v[170:173], v[94:97]
	v_mfma_f32_16x16x32_bf16 v[86:89], v[130:133], v[220:223], v[86:89]
	v_mfma_f32_16x16x32_bf16 v[74:77], v[138:141], v[220:223], v[74:77]
	v_mfma_f32_16x16x32_bf16 v[82:85], v[130:133], v[228:231], v[82:85]
	v_mfma_f32_16x16x32_bf16 v[70:73], v[138:141], v[228:231], v[70:73]
	v_mfma_f32_16x16x32_bf16 v[118:121], v[134:137], v[166:169], v[118:121]
	v_mfma_f32_16x16x32_bf16 v[110:113], v[142:145], v[166:169], v[110:113]
	v_mfma_f32_16x16x32_bf16 v[102:105], v[134:137], v[174:177], v[102:105]
	v_mfma_f32_16x16x32_bf16 v[94:97], v[142:145], v[174:177], v[94:97]
	v_mfma_f32_16x16x32_bf16 v[86:89], v[134:137], v[224:227], v[86:89]
	v_mfma_f32_16x16x32_bf16 v[74:77], v[142:145], v[224:227], v[74:77]
	v_mfma_f32_16x16x32_bf16 v[82:85], v[134:137], v[232:235], v[82:85]
	v_mfma_f32_16x16x32_bf16 v[70:73], v[142:145], v[232:235], v[70:73]
	s_setprio 0
	s_setprio 1
	v_mfma_f32_16x16x32_bf16 v[126:129], v[146:149], v[162:165], v[126:129]
	v_mfma_f32_16x16x32_bf16 v[122:125], v[154:157], v[162:165], v[122:125]
	v_mfma_f32_16x16x32_bf16 v[114:117], v[146:149], v[170:173], v[114:117]
	v_mfma_f32_16x16x32_bf16 v[106:109], v[154:157], v[170:173], v[106:109]
	v_mfma_f32_16x16x32_bf16 v[98:101], v[146:149], v[220:223], v[98:101]
	v_mfma_f32_16x16x32_bf16 v[90:93], v[154:157], v[220:223], v[90:93]
	v_mfma_f32_16x16x32_bf16 v[78:81], v[146:149], v[228:231], v[78:81]
	v_mfma_f32_16x16x32_bf16 v[66:69], v[154:157], v[228:231], v[66:69]
	v_mfma_f32_16x16x32_bf16 v[126:129], v[150:153], v[166:169], v[126:129]
	v_mfma_f32_16x16x32_bf16 v[122:125], v[158:161], v[166:169], v[122:125]
	v_mfma_f32_16x16x32_bf16 v[114:117], v[150:153], v[174:177], v[114:117]
	v_mfma_f32_16x16x32_bf16 v[106:109], v[158:161], v[174:177], v[106:109]
	v_mfma_f32_16x16x32_bf16 v[98:101], v[150:153], v[224:227], v[98:101]
	v_mfma_f32_16x16x32_bf16 v[90:93], v[158:161], v[224:227], v[90:93]
	v_mfma_f32_16x16x32_bf16 v[78:81], v[150:153], v[232:235], v[78:81]
	v_mfma_f32_16x16x32_bf16 v[66:69], v[158:161], v[232:235], v[66:69]
	s_setprio 0
	s_barrier
; #define PG8_STAGE(bufoff, gbase, voff) do { _Pragma("unroll") for (int _i = 0; _i < 2; ++_i) \
;         __builtin_amdgcn_global_load_lds((const unsigned*)((const char*)(gbase) + (voff)[_i]), (LAS unsigned*)(lds + (bufoff) + ldsw + _i * 8192), 16, 0, 0); } while (0)
; #define PG8_LDA(dst, b, h) do { _Pragma("unroll") for (int m = 0; m < 4; ++m) _Pragma("unroll") for (int k = 0; k < 2; ++k) dst[m][k] = *(const LAS bf16x8*)(lds + PG8_SA(b, h) + aoff + m * 2048 + k * 1024); } while (0)
; #define PG8_MMA(ai, bj, At, Bt) do { __builtin_amdgcn_s_setprio(1); _Pragma("unroll") for (int m = 0; m < 4; ++m) _Pragma("unroll") for (int n = 0; n < 2; ++n) _Pragma("unroll") for (int k = 0; k < 2; ++k) \
;         acc[ai][bj][m][n] = __builtin_amdgcn_mfma_f32_16x16x32_bf16(Bt[n][k], At[m][k], acc[ai][bj][m][n], 0, 0, 0); __builtin_amdgcn_s_setprio(0); } while (0)
; #define PG8_WAIT_V(n) asm volatile("s_waitcnt vmcnt(" #n ")" ::: "memory")
; #define PG8_WAIT_L(n) asm volatile("s_waitcnt lgkmcnt(" #n ")" ::: "memory")
; #define PG8_BAR __builtin_amdgcn_s_barrier()
; #define PG8_SCHED __builtin_amdgcn_sched_barrier(0)
; __device__ __forceinline__ void gemm_phase(LAS unsigned char* lds, const Gemm g, const StaticOrder& S, const Epi& E, const int tid) {
;     ...
;             PG8_LDA(At, 1, 1); PG8_STAGE(PG8_SB(1, 0), b3, voffB); PG8_STAGE(PG8_SB(1, 1), b3 + hstepB, voffB); PG8_STAGE(PG8_SA(1, 0), a3, voffA);
;             PG8_WAIT_V(8); PG8_WAIT_L(0); PG8_BAR; PG8_MMA(1, 0, At, B0); PG8_MMA(1, 1, At, B1); PG8_BAR; PG8_SCHED;
;         }
	s_add_i32 s4, s24, s72
	v_lshl_add_u64 v[188:189], v[188:189], 0, s[30:31]
	s_mov_b32 m0, s4
	ds_read_b128 v[162:165], v219 offset:49152
	ds_read_b128 v[166:169], v219 offset:50176
	ds_read_b128 v[170:173], v219 offset:51200
	ds_read_b128 v[174:177], v219 offset:52224
	ds_read_b128 v[220:223], v219 offset:53248
	ds_read_b128 v[224:227], v219 offset:54272
	ds_read_b128 v[228:231], v219 offset:55296
	ds_read_b128 v[232:235], v219 offset:56320
	global_load_lds_dwordx4 v[188:189], off
	v_lshl_add_u64 v[188:189], v[236:237], 0, s[30:31]
	s_add_i32 m0, s4, 0x2000
	s_add_i32 s4, s25, s72
	global_load_lds_dwordx4 v[188:189], off
	v_lshl_add_u64 v[188:189], v[238:239], 0, s[30:31]
	s_mov_b32 m0, s4
	s_nop 0
	global_load_lds_dwordx4 v[188:189], off
	v_lshl_add_u64 v[188:189], v[240:241], 0, s[30:31]
	s_add_i32 m0, s4, 0x2000
	s_nop 0
	global_load_lds_dwordx4 v[188:189], off
	v_lshl_add_u64 v[188:189], v[242:243], 0, s[30:31]
	s_mov_b32 m0, s97
	s_nop 0
	global_load_lds_dwordx4 v[188:189], off
	v_lshl_add_u64 v[188:189], v[244:245], 0, s[30:31]
	s_mov_b32 m0, s14
	s_nop 0
	global_load_lds_dwordx4 v[188:189], off
	s_waitcnt vmcnt(8)
	s_waitcnt lgkmcnt(0)
	s_barrier
	s_setprio 1
	s_waitcnt lgkmcnt(0)
	v_mfma_f32_16x16x32_bf16 v[54:57], v[130:133], v[162:165], v[54:57]
	v_mfma_f32_16x16x32_bf16 v[46:49], v[138:141], v[162:165], v[46:49]
	v_mfma_f32_16x16x32_bf16 v[38:41], v[130:133], v[170:173], v[38:41]
	v_mfma_f32_16x16x32_bf16 v[30:33], v[138:141], v[170:173], v[30:33]
	v_mfma_f32_16x16x32_bf16 v[22:25], v[130:133], v[220:223], v[22:25]
	v_mfma_f32_16x16x32_bf16 v[18:21], v[138:141], v[220:223], v[18:21]
	v_mfma_f32_16x16x32_bf16 v[14:17], v[130:133], v[228:231], v[14:17]
	v_mfma_f32_16x16x32_bf16 v[6:9], v[138:141], v[228:231], v[6:9]
	v_mfma_f32_16x16x32_bf16 v[54:57], v[134:137], v[166:169], v[54:57]
	v_mfma_f32_16x16x32_bf16 v[46:49], v[142:145], v[166:169], v[46:49]
	v_mfma_f32_16x16x32_bf16 v[38:41], v[134:137], v[174:177], v[38:41]
	v_mfma_f32_16x16x32_bf16 v[30:33], v[142:145], v[174:177], v[30:33]
	v_mfma_f32_16x16x32_bf16 v[22:25], v[134:137], v[224:227], v[22:25]
	v_mfma_f32_16x16x32_bf16 v[18:21], v[142:145], v[224:227], v[18:21]
	v_mfma_f32_16x16x32_bf16 v[14:17], v[134:137], v[232:235], v[14:17]
	v_mfma_f32_16x16x32_bf16 v[6:9], v[142:145], v[232:235], v[6:9]
	s_setprio 0
	s_setprio 1
	v_mfma_f32_16x16x32_bf16 v[62:65], v[146:149], v[162:165], v[62:65]
	v_mfma_f32_16x16x32_bf16 v[58:61], v[154:157], v[162:165], v[58:61]
	v_mfma_f32_16x16x32_bf16 v[50:53], v[146:149], v[170:173], v[50:53]
	v_mfma_f32_16x16x32_bf16 v[42:45], v[154:157], v[170:173], v[42:45]
	v_mfma_f32_16x16x32_bf16 v[34:37], v[146:149], v[220:223], v[34:37]
	v_mfma_f32_16x16x32_bf16 v[26:29], v[154:157], v[220:223], v[26:29]
	v_mfma_f32_16x16x32_bf16 v[10:13], v[146:149], v[228:231], v[10:13]
	v_mfma_f32_16x16x32_bf16 v[2:5], v[154:157], v[228:231], v[2:5]
	v_mfma_f32_16x16x32_bf16 v[62:65], v[150:153], v[166:169], v[62:65]
	v_mfma_f32_16x16x32_bf16 v[58:61], v[158:161], v[166:169], v[58:61]
	v_mfma_f32_16x16x32_bf16 v[50:53], v[150:153], v[174:177], v[50:53]
	v_mfma_f32_16x16x32_bf16 v[42:45], v[158:161], v[174:177], v[42:45]
	v_mfma_f32_16x16x32_bf16 v[34:37], v[150:153], v[224:227], v[34:37]
	v_mfma_f32_16x16x32_bf16 v[26:29], v[158:161], v[224:227], v[26:29]
	v_mfma_f32_16x16x32_bf16 v[10:13], v[150:153], v[232:235], v[10:13]
	v_mfma_f32_16x16x32_bf16 v[2:5], v[158:161], v[232:235], v[2:5]
	s_setprio 0
	s_barrier
	s_add_u32 s2, s2, 0x100
	s_addc_u32 s3, s3, 0
	s_add_u32 s18, s18, 0x100
	s_addc_u32 s19, s19, 0
	s_cmp_ge_u32 s29, s96
	s_mov_b32 s4, s29
	s_cbranch_scc0 .LBB0_530
